# barrier poll spin cap raised to the baseline's 2^18 (robustness only, same timing path)
# speedup vs baseline: 1.0028x; 1.0028x over previous
; __device__ __forceinline__ unsigned xb_ld(unsigned* p)              { return __hip_atomic_load(p, __ATOMIC_RELAXED, __HIP_MEMORY_SCOPE_AGENT); }
; #define XB_SPIN(cond, bar) do { unsigned _sp = 0; while (cond) { __builtin_amdgcn_s_sleep(1); \
;     if ((++_sp & 255u) == 0u) { if (xb_ld(&(bar)[XB_TMO])) break; if (_sp > XB_SPIN_CAP) { atomicAdd(&(bar)[XB_TMO], 1u); break; } } } } while (0)
; __device__ __forceinline__ void xcd_barrier(const XcdBarrier& b, const bool is_t0) {
;     ...
;             XB_SPIN(xb_ld(&bar[XB_XGEN(b.x)]) == gen, bar);
.Lxb1_poll:
	s_mov_b32 s18, 0x40000

; __device__ __forceinline__ unsigned xb_ld(unsigned* p)              { return __hip_atomic_load(p, __ATOMIC_RELAXED, __HIP_MEMORY_SCOPE_AGENT); }
; #define XB_SPIN(cond, bar) do { unsigned _sp = 0; while (cond) { __builtin_amdgcn_s_sleep(1); \
;     if ((++_sp & 255u) == 0u) { if (xb_ld(&(bar)[XB_TMO])) break; if (_sp > XB_SPIN_CAP) { atomicAdd(&(bar)[XB_TMO], 1u); break; } } } } while (0)
; __device__ __forceinline__ void xcd_barrier(const XcdBarrier& b, const bool is_t0) {
;     ...
;             XB_SPIN(xb_ld(&bar[XB_XGEN(b.x)]) == gen, bar);
.Lxb2_poll:
	s_mov_b32 s10, 0x40000
